# phase 0: adaLN items moved to the last 96 workgroups (fewest weight-transpose iterations) instead of the first 96
# speedup vs baseline: 1.1426x; 1.0090x over previous
; DI void phase0(KP p, char* lds) {
;     ...
;   const int hb = tid >> 8, tq = tid & 255;
;   float* sl = (float*)(lds + hb * HALF_LDS);
;   float* mod = (float*)(ws + WS_MOD);
;   const int kg = tq >> 5, cn = tq & 31;
;   for (int it = 2 * blockIdx.x + hb; it < 192; it += 2 * gridDim.x) {
;     const int l = it / 96, n = (it % 96) * 32 + cn;
.LBB0_505:
	s_or_b64 exec, exec, s[4:5]
	v_ashrrev_i32_e32 v0, 8, v2
	v_readlane_b32 s2, v253, 7
	s_nop 1
	s_sub_i32 s2, 0x1fe, s2
	v_add_u32_e32 v71, s2, v0
	s_movk_i32 s2, 0xc0
	v_cmp_gt_i32_e32 vcc, s2, v71
	s_and_saveexec_b64 s[42:43], vcc
	s_cbranch_execz .LBB0_514
	s_load_dwordx2 s[48:49], s[0:1], 0x8
	s_load_dwordx4 s[44:47], s[0:1], 0x28
	v_and_b32_e32 v73, 31, v2
	s_mov_b32 s2, 0x11000
	v_lshrrev_b32_e32 v4, 5, v70
	v_mul_i32_i24_e32 v3, 0x11000, v0
	v_mad_i32_i24 v0, v0, s2, 0
	v_lshlrev_b32_e32 v5, 2, v73
	v_bfe_u32 v74, v2, 5, 3
	v_lshlrev_b32_e32 v2, 7, v4
	v_lshl_add_u32 v104, v4, 8, v0
	v_add_u32_e32 v6, v0, v5
	v_lshl_add_u32 v105, v70, 2, v0
	v_mul_u32_u24_e32 v0, 0x880, v4
	v_or3_b32 v2, v3, v2, v5
	v_lshlrev_b32_e32 v72, 6, v4
	v_or_b32_e32 v106, 0xffffff00, v70
	v_mov_b32_e32 v75, v1
	v_add_u32_e32 v107, 0, v2
	s_mov_b64 s[50:51], 0
	v_add_u32_e32 v108, v6, v0
